# adds: x f32->bf16 conversion loop rotated so the next iteration's loads are in flight during convert+store
# speedup vs baseline: 1.0012x; 1.0012x over previous
; DI unsigned cvt_pk_bf16(float lo, float hi) { unsigned r; asm("v_cvt_pk_bf16_f32 %0, %1, %2" : "=v"(r) : "v"(lo), "v"(hi)); return r; }
; __device__ void phase_prep(const Params& p, unsigned char* shm) {
;     ...
;     for (size_t i = (size_t)b * 512 + tid; i < (size_t)T * DM / 8; i += (size_t)nb * 512) {
;         const size_t e = i * 8; const int r = (int)(e / DM), c = (int)(e % DM);
;         const float* src = xrow(p, r) + c;
;         const f32x4 a = *(const f32x4*)src, bb = *(const f32x4*)(src + 4);
;         u32x4 w; w.x = cvt_pk_bf16(a[0], a[1]); w.y = cvt_pk_bf16(a[2], a[3]); w.z = cvt_pk_bf16(bb[0], bb[1]); w.w = cvt_pk_bf16(bb[2], bb[3]);
;         *(u32x4*)(XB + e) = w;
;     }
.LBB0_74:
	s_ashr_i32 s3, s2, 31
	v_mov_b32_e32 v1, 0
	s_lshl_b64 s[0:1], s[2:3], 9
	v_mov_b32_e32 v137, v1
	v_lshl_add_u64 v[2:3], s[0:1], 0, v[136:137]
	s_mov_b64 s[0:1], 0xa00000
	v_cmp_gt_u64_e32 vcc, s[0:1], v[2:3]
	s_and_saveexec_b64 s[22:23], vcc
	s_cbranch_execz .LBB0_81
	s_ashr_i32 s1, s30, 31
	s_mov_b32 s0, s30
	s_lshl_b64 s[52:53], s[2:3], 14
	v_lshlrev_b64 v[4:5], 5, v[136:137]
	s_lshl_b64 s[24:25], s[0:1], 9
	v_lshl_add_u64 v[4:5], s[52:53], 0, v[4:5]
	s_lshl_b64 s[52:53], s[0:1], 14
	s_lshl_b64 s[54:55], s[2:3], 13
	s_add_u32 s54, s26, s54
	s_addc_u32 s55, s27, s55
	v_lshl_add_u64 v[6:7], v[136:137], 4, s[54:55]
	s_mov_b64 s[54:55], 0x28000000
	s_lshl_b64 s[56:57], s[2:3], 12
	s_brev_b32 s62, 63
	v_lshl_add_u64 v[6:7], v[6:7], 0, s[54:55]
	s_lshl_b64 s[54:55], s[0:1], 13
	v_lshl_add_u64 v[8:9], v[136:137], 3, s[56:57]
	s_lshl_b64 s[56:57], s[0:1], 12
	s_mov_b64 s[58:59], 0
	s_mov_b64 s[60:61], 0x1fffff
	s_movk_i32 s63, 0x1fff
	s_mov_b64 s[64:65], 0x9fffff
	s_branch .Lxc_pro
.Lxc_pro:
	v_cmp_lt_u64_e32 vcc, s[60:61], v[2:3]
	s_and_saveexec_b64 s[0:1], vcc
	s_xor_b64 s[66:67], exec, s[0:1]
	v_lshl_add_u64 v[10:11], v[4:5], 0, s[62:63]
	v_and_b32_e32 v11, 0x1fff, v11
	v_and_b32_e32 v10, 0xffffe000, v10
	v_lshl_add_u64 v[10:11], s[6:7], 0, v[10:11]
	s_andn2_saveexec_b64 s[66:67], s[66:67]
	s_cbranch_execz .Lxc_j_p
	v_and_b32_e32 v0, 0x3ffe000, v4
	v_lshl_add_u64 v[10:11], s[4:5], 0, v[0:1]
.Lxc_j_p:
	s_or_b64 exec, exec, s[66:67]
	v_and_b32_e32 v0, 0x7f8, v8
	v_lshlrev_b32_e32 v0, 2, v0
	v_lshl_add_u64 v[14:15], v[10:11], 0, v[0:1]
	global_load_dwordx4 v[18:21], v[14:15], off
	global_load_dwordx4 v[22:25], v[14:15], off offset:16
	v_lshl_add_u64 v[2:3], v[2:3], 0, s[24:25]
	v_cmp_lt_u64_e32 vcc, s[64:65], v[2:3]
	v_lshl_add_u64 v[4:5], v[4:5], 0, s[52:53]
	s_or_b64 s[58:59], vcc, s[58:59]
	v_lshl_add_u64 v[8:9], v[8:9], 0, s[56:57]
	s_waitcnt vmcnt(0)
.Lxc_loop:
	s_waitcnt vmcnt(1)
	v_cvt_pk_bf16_f32 v26, v18, v19
	v_cvt_pk_bf16_f32 v27, v20, v21
	v_cvt_pk_bf16_f32 v28, v22, v23
	v_cvt_pk_bf16_f32 v29, v24, v25
	s_mov_b64 s[100:101], s[58:59]
	s_mov_b64 s[98:99], exec
	s_andn2_b64 exec, exec, s[100:101]
	s_cbranch_execz .Lxc_nonext
	v_cmp_lt_u64_e32 vcc, s[60:61], v[2:3]
	s_and_saveexec_b64 s[0:1], vcc
	s_xor_b64 s[66:67], exec, s[0:1]
	v_lshl_add_u64 v[10:11], v[4:5], 0, s[62:63]
	v_and_b32_e32 v11, 0x1fff, v11
	v_and_b32_e32 v10, 0xffffe000, v10
	v_lshl_add_u64 v[10:11], s[6:7], 0, v[10:11]
	s_andn2_saveexec_b64 s[66:67], s[66:67]
	s_cbranch_execz .Lxc_j_l
	v_and_b32_e32 v0, 0x3ffe000, v4
	v_lshl_add_u64 v[10:11], s[4:5], 0, v[0:1]
.Lxc_j_l:
	s_or_b64 exec, exec, s[66:67]
	v_and_b32_e32 v0, 0x7f8, v8
	v_lshlrev_b32_e32 v0, 2, v0
	v_lshl_add_u64 v[14:15], v[10:11], 0, v[0:1]
	global_load_dwordx4 v[18:21], v[14:15], off
	global_load_dwordx4 v[22:25], v[14:15], off offset:16
	v_lshl_add_u64 v[2:3], v[2:3], 0, s[24:25]
	v_cmp_lt_u64_e32 vcc, s[64:65], v[2:3]
	v_lshl_add_u64 v[4:5], v[4:5], 0, s[52:53]
	s_or_b64 s[58:59], vcc, s[58:59]
	v_lshl_add_u64 v[8:9], v[8:9], 0, s[56:57]
.Lxc_nonext:
	s_mov_b64 exec, s[98:99]
	global_store_dwordx4 v[6:7], v[26:29], off
	v_lshl_add_u64 v[6:7], v[6:7], 0, s[54:55]
	s_andn2_b64 exec, exec, s[100:101]
	s_cbranch_execnz .Lxc_loop
